# P2 HGRN prompt k-step: multiplicative decay scans fused into v_mul_f32_dpp (one op per scan element instead of mov+dpp-mov+mul), on top of v8
# speedup vs baseline: 1.0153x; 1.0011x over previous
.Lp2h_mid:
	ds_read_b128 v[46:49], v41
	ds_read_b128 v[52:55], v41 offset:16
	v_mul_f32_e64 v41, |v33|, s80
	v_exp_f32_e32 v80, v41
	v_mul_f32_e64 v41, |v32|, s80
	v_exp_f32_e32 v81, v41
	v_mul_f32_e64 v41, |v31|, s80
	v_exp_f32_e32 v82, v41
	v_mul_f32_e64 v41, |v30|, s80
	v_exp_f32_e32 v83, v41
	v_mul_f32_e64 v41, |v29|, s80
	v_exp_f32_e32 v84, v41
	v_mul_f32_e64 v41, |v28|, s80
	v_exp_f32_e32 v85, v41
	v_mul_f32_e64 v41, |v27|, s80
	v_exp_f32_e32 v86, v41
	v_mul_f32_e64 v41, |v26|, s80
	v_exp_f32_e32 v87, v41
	v_add_f32_e32 v41, 1.0, v80
	v_rcp_f32_e32 v88, v41
	v_add_f32_e32 v41, 1.0, v81
	v_rcp_f32_e32 v89, v41
	v_add_f32_e32 v41, 1.0, v82
	v_rcp_f32_e32 v90, v41
	v_add_f32_e32 v41, 1.0, v83
	v_rcp_f32_e32 v91, v41
	v_add_f32_e32 v41, 1.0, v84
	v_rcp_f32_e32 v92, v41
	v_add_f32_e32 v41, 1.0, v85
	v_rcp_f32_e32 v93, v41
	v_add_f32_e32 v41, 1.0, v86
	v_pk_mul_f32 v[80:81], v[80:81], v[88:89]
	v_cmp_nle_f32_e32 vcc, 0, v33
	v_rcp_f32_e32 v94, v41
	v_add_f32_e32 v41, 1.0, v87
	v_cndmask_b32_e32 v33, v80, v88, vcc
	s_waitcnt lgkmcnt(1)
	v_pk_add_f32 v[96:97], v[46:47], 1.0 op_sel_hi:[1,0] neg_lo:[1,0] neg_hi:[1,0]
	v_cmp_nle_f32_e64 s[0:1], 0, v32
	v_rcp_f32_e32 v95, v41
	v_mul_f32_e32 v41, v96, v33
	v_cndmask_b32_e64 v33, v89, v81, s[0:1]
	v_cndmask_b32_e32 v32, v88, v80, vcc
	v_cndmask_b32_e64 v51, v81, v89, s[0:1]
	v_pk_fma_f32 v[32:33], v[96:97], v[32:33], v[46:47]
	v_pk_mul_f32 v[46:47], v[82:83], v[90:91]
	v_cmp_nle_f32_e32 vcc, 0, v31
	v_cmp_nle_f32_e64 s[0:1], 0, v30
	v_pk_add_f32 v[80:81], v[48:49], 1.0 op_sel_hi:[1,0] neg_lo:[1,0] neg_hi:[1,0]
	v_cndmask_b32_e32 v31, v46, v90, vcc
	v_cndmask_b32_e32 v30, v90, v46, vcc
	v_cndmask_b32_e64 v46, v47, v91, s[0:1]
	v_mul_f32_e32 v56, v80, v31
	v_cndmask_b32_e64 v31, v91, v47, s[0:1]
	v_mul_f32_e32 v71, v81, v46
	v_pk_mul_f32 v[46:47], v[84:85], v[92:93]
	v_cmp_nle_f32_e32 vcc, 0, v29
	v_cmp_nle_f32_e64 s[0:1], 0, v28
	v_pk_fma_f32 v[30:31], v[80:81], v[30:31], v[48:49]
	v_cndmask_b32_e32 v29, v46, v92, vcc
	s_waitcnt lgkmcnt(0)
	v_pk_add_f32 v[48:49], v[52:53], 1.0 op_sel_hi:[1,0] neg_lo:[1,0] neg_hi:[1,0]
	v_cndmask_b32_e32 v28, v92, v46, vcc
	v_cndmask_b32_e64 v46, v47, v93, s[0:1]
	v_mul_f32_e32 v73, v48, v29
	v_cndmask_b32_e64 v29, v93, v47, s[0:1]
	v_mul_f32_e32 v75, v49, v46
	v_pk_mul_f32 v[46:47], v[86:87], v[94:95]
	v_cmp_nle_f32_e32 vcc, 0, v27
	v_pk_fma_f32 v[28:29], v[48:49], v[28:29], v[52:53]
	v_pk_add_f32 v[48:49], v[54:55], 1.0 op_sel_hi:[1,0] neg_lo:[1,0] neg_hi:[1,0]
	v_cndmask_b32_e32 v27, v46, v94, vcc
	v_cmp_nle_f32_e64 s[0:1], 0, v26
	v_mul_f32_e32 v77, v48, v27
	v_cndmask_b32_e32 v26, v94, v46, vcc
	v_cndmask_b32_e64 v27, v95, v47, s[0:1]
	v_cndmask_b32_e64 v52, v47, v95, s[0:1]
	v_and_b32_e32 v47, 0xffff0000, v42
	v_pk_fma_f32 v[26:27], v[48:49], v[26:27], v[54:55]
	v_mul_f32_e32 v48, 0xbfb8aa3b, v47
	v_exp_f32_e32 v48, v48
	v_mul_f32_e32 v79, v49, v52
	v_lshlrev_b32_e32 v46, 16, v42
	v_and_b32_e32 v49, 0xffff0000, v43
	v_add_f32_e32 v52, 1.0, v48
	v_lshlrev_b32_e32 v48, 16, v43
	v_mul_f32_e32 v43, 0xbfb8aa3b, v48
	v_mul_f32_e32 v42, 0xbfb8aa3b, v46
	v_exp_f32_e32 v53, v43
	v_mul_f32_e32 v43, 0xbfb8aa3b, v49
	v_exp_f32_e32 v42, v42
	v_exp_f32_e32 v54, v43
	v_rcp_f32_e32 v43, v52
	v_add_f32_e32 v52, 1.0, v53
	v_add_f32_e32 v42, 1.0, v42
	v_add_f32_e32 v53, 1.0, v54
	v_rcp_f32_e32 v42, v42
	v_rcp_f32_e32 v52, v52
	v_rcp_f32_e32 v53, v53
	v_cndmask_b32_e64 v32, 1.0, v32, s[42:43]
	v_pk_mul_f32 v[42:43], v[42:43], v[46:47]
	v_cndmask_b32_e64 v33, 1.0, v33, s[42:43]
	v_pk_mul_f32 v[46:47], v[52:53], v[48:49]
	v_cndmask_b32_e64 v30, 1.0, v30, s[42:43]
	v_cndmask_b32_e64 v31, 1.0, v31, s[42:43]
	v_mul_f32_dpp v32, v32, v32 row_shr:1 row_mask:0xf bank_mask:0xf
	v_cndmask_b32_e64 v28, 1.0, v28, s[42:43]
	v_cndmask_b32_e64 v29, 1.0, v29, s[42:43]
	v_mul_f32_dpp v33, v33, v33 row_shr:1 row_mask:0xf bank_mask:0xf
	v_cndmask_b32_e64 v26, 1.0, v26, s[42:43]
	v_cndmask_b32_e64 v27, 1.0, v27, s[42:43]
	v_mul_f32_dpp v30, v30, v30 row_shr:1 row_mask:0xf bank_mask:0xf
	v_and_b32_e32 v55, 0xffff0000, v44
	v_mul_f32_e32 v80, 0xbfb8aa3b, v55
	v_mul_f32_dpp v31, v31, v31 row_shr:1 row_mask:0xf bank_mask:0xf
	v_exp_f32_e32 v80, v80
	v_lshlrev_b32_e32 v54, 16, v44
	v_mul_f32_dpp v28, v28, v28 row_shr:1 row_mask:0xf bank_mask:0xf
	v_add_f32_e32 v82, 1.0, v80
	v_lshlrev_b32_e32 v80, 16, v45
	v_mul_f32_dpp v29, v29, v29 row_shr:1 row_mask:0xf bank_mask:0xf
	v_and_b32_e32 v81, 0xffff0000, v45
	v_mul_f32_e32 v45, 0xbfb8aa3b, v80
	v_mul_f32_dpp v26, v26, v26 row_shr:1 row_mask:0xf bank_mask:0xf
	v_mul_f32_e32 v44, 0xbfb8aa3b, v54
	v_exp_f32_e32 v83, v45
	v_mul_f32_dpp v27, v27, v27 row_shr:1 row_mask:0xf bank_mask:0xf
	v_mul_f32_e32 v45, 0xbfb8aa3b, v81
	v_exp_f32_e32 v44, v44
	v_mul_f32_dpp v32, v32, v32 row_shr:2 row_mask:0xf bank_mask:0xf
	v_exp_f32_e32 v84, v45
	v_add_f32_e32 v44, 1.0, v44
	v_mul_f32_dpp v33, v33, v33 row_shr:2 row_mask:0xf bank_mask:0xf
	v_rcp_f32_e32 v45, v82
	v_add_f32_e32 v82, 1.0, v83
	v_mul_f32_dpp v30, v30, v30 row_shr:2 row_mask:0xf bank_mask:0xf
	v_add_f32_e32 v83, 1.0, v84
	v_rcp_f32_e32 v44, v44
	v_mul_f32_dpp v31, v31, v31 row_shr:2 row_mask:0xf bank_mask:0xf
	v_rcp_f32_e32 v82, v82
	v_rcp_f32_e32 v83, v83
	v_mul_f32_dpp v28, v28, v28 row_shr:2 row_mask:0xf bank_mask:0xf
	v_pk_mul_f32 v[44:45], v[44:45], v[54:55]
	v_pk_mul_f32 v[48:49], v[82:83], v[80:81]
	v_mul_f32_dpp v29, v29, v29 row_shr:2 row_mask:0xf bank_mask:0xf
	v_mul_f32_e32 v51, v97, v51
	v_cndmask_b32_e64 v41, 0, v41, s[42:43]
	v_mul_f32_dpp v26, v26, v26 row_shr:2 row_mask:0xf bank_mask:0xf
	v_cndmask_b32_e64 v51, 0, v51, s[42:43]
	v_cndmask_b32_e64 v56, 0, v56, s[42:43]
	v_mul_f32_dpp v27, v27, v27 row_shr:2 row_mask:0xf bank_mask:0xf
	v_cndmask_b32_e64 v71, 0, v71, s[42:43]
	v_cndmask_b32_e64 v73, 0, v73, s[42:43]
	v_mul_f32_dpp v32, v32, v32 row_shr:4 row_mask:0xf bank_mask:0xf
	v_cndmask_b32_e64 v75, 0, v75, s[42:43]
	v_cndmask_b32_e64 v77, 0, v77, s[42:43]
	v_mul_f32_dpp v33, v33, v33 row_shr:4 row_mask:0xf bank_mask:0xf
	v_cndmask_b32_e64 v79, 0, v79, s[42:43]
	v_cndmask_b32_e64 v49, 0, v49, s[42:43]
	v_mul_f32_dpp v30, v30, v30 row_shr:4 row_mask:0xf bank_mask:0xf
	v_cndmask_b32_e64 v48, 0, v48, s[42:43]
	v_cndmask_b32_e64 v47, 0, v47, s[42:43]
	v_mul_f32_dpp v31, v31, v31 row_shr:4 row_mask:0xf bank_mask:0xf
	v_cndmask_b32_e64 v46, 0, v46, s[42:43]
	v_cndmask_b32_e64 v45, 0, v45, s[42:43]
	v_mul_f32_dpp v28, v28, v28 row_shr:4 row_mask:0xf bank_mask:0xf
	v_cndmask_b32_e64 v44, 0, v44, s[42:43]
	v_cndmask_b32_e64 v43, 0, v43, s[42:43]
	v_mul_f32_dpp v29, v29, v29 row_shr:4 row_mask:0xf bank_mask:0xf
	v_cndmask_b32_e64 v42, 0, v42, s[42:43]
	s_nop 0
	v_mul_f32_dpp v26, v26, v26 row_shr:4 row_mask:0xf bank_mask:0xf
	v_mul_f32_dpp v27, v27, v27 row_shr:4 row_mask:0xf bank_mask:0xf
	v_mul_f32_dpp v32, v32, v32 row_shr:8 row_mask:0xf bank_mask:0xf
	v_mul_f32_dpp v33, v33, v33 row_shr:8 row_mask:0xf bank_mask:0xf
	v_mul_f32_dpp v30, v30, v30 row_shr:8 row_mask:0xf bank_mask:0xf
	v_mul_f32_dpp v31, v31, v31 row_shr:8 row_mask:0xf bank_mask:0xf
	v_mul_f32_dpp v28, v28, v28 row_shr:8 row_mask:0xf bank_mask:0xf
	v_mul_f32_dpp v29, v29, v29 row_shr:8 row_mask:0xf bank_mask:0xf
	v_mul_f32_dpp v26, v26, v26 row_shr:8 row_mask:0xf bank_mask:0xf
	v_mul_f32_dpp v27, v27, v27 row_shr:8 row_mask:0xf bank_mask:0xf
	v_mul_f32_dpp v32, v32, v32 row_bcast:15 row_mask:0xa bank_mask:0xf
	v_mul_f32_dpp v33, v33, v33 row_bcast:15 row_mask:0xa bank_mask:0xf
	v_max_f32_e32 v53, 0x554ad2e, v33
	v_rcp_f32_e32 v85, v53
	v_mul_f32_dpp v30, v30, v30 row_bcast:15 row_mask:0xa bank_mask:0xf
	v_max_f32_e32 v54, 0x554ad2e, v30
	v_rcp_f32_e32 v86, v54
	v_mul_f32_dpp v31, v31, v31 row_bcast:15 row_mask:0xa bank_mask:0xf
	v_max_f32_e32 v55, 0x554ad2e, v31
	v_rcp_f32_e32 v87, v55
	v_mul_f32_dpp v28, v28, v28 row_bcast:15 row_mask:0xa bank_mask:0xf
	v_max_f32_e32 v80, 0x554ad2e, v28
	v_rcp_f32_e32 v88, v80
	v_mul_f32_dpp v29, v29, v29 row_bcast:15 row_mask:0xa bank_mask:0xf
	v_max_f32_e32 v81, 0x554ad2e, v29
	v_rcp_f32_e32 v89, v81
	v_mul_f32_dpp v26, v26, v26 row_bcast:15 row_mask:0xa bank_mask:0xf
	v_max_f32_e32 v82, 0x554ad2e, v26
	v_rcp_f32_e32 v90, v82
	v_mul_f32_dpp v27, v27, v27 row_bcast:15 row_mask:0xa bank_mask:0xf
	v_max_f32_e32 v52, 0x554ad2e, v32
	v_max_f32_e32 v83, 0x554ad2e, v27
	v_rcp_f32_e32 v84, v52
	v_rcp_f32_e32 v91, v83
	v_readlane_b32 s0, v52, 31
	v_readlane_b32 s1, v52, 63
	v_mul_f32_e32 v41, v41, v84
	v_mov_b32_e32 v27, s0
	v_mov_b32_e32 v26, s1
	v_readlane_b32 s0, v53, 31
	v_readlane_b32 s1, v53, 63
	v_cndmask_b32_e64 v26, v26, v27, s[2:3]
	v_mov_b32_e32 v28, s0
	v_mov_b32_e32 v27, s1
	v_readlane_b32 s0, v54, 31
	v_readlane_b32 s1, v54, 63
	v_pk_mul_f32 v[42:43], v[42:43], v[52:53]
	v_mul_f32_e32 v51, v51, v85
	v_mul_f32_e32 v53, v56, v86
	v_pk_mul_f32 v[46:47], v[46:47], v[54:55]
	v_mul_f32_e32 v54, v71, v87
	v_mul_f32_e32 v71, v73, v88
	v_pk_mul_f32 v[44:45], v[44:45], v[80:81]
	v_mul_f32_e32 v75, v75, v89
	v_mul_f32_e32 v77, v77, v90
	v_pk_mul_f32 v[48:49], v[48:49], v[82:83]
	v_mul_f32_e32 v79, v79, v91
	v_cvt_pk_bf16_f32 v42, v42, v43
	v_cvt_pk_bf16_f32 v43, v46, v47
	v_cvt_pk_bf16_f32 v44, v44, v45
	v_cvt_pk_bf16_f32 v45, v48, v49
	v_cvt_pk_bf16_f32 v46, v41, v51
	v_cvt_pk_bf16_f32 v47, v53, v54
	v_cvt_pk_bf16_f32 v48, v71, v75
	v_cvt_pk_bf16_f32 v49, v77, v79
	v_cndmask_b32_e64 v27, v27, v28, s[2:3]
	v_mov_b32_e32 v28, s1
	v_mov_b32_e32 v29, s0
	v_readlane_b32 s0, v55, 31
	v_readlane_b32 s1, v55, 63
	v_cndmask_b32_e64 v28, v28, v29, s[2:3]
	v_mov_b32_e32 v30, s0
	v_mov_b32_e32 v29, s1
	v_readlane_b32 s0, v80, 31
	v_readlane_b32 s1, v80, 63
	v_mfma_f32_32x32x16_bf16 v[2:17], v[46:49], v[42:45], v[2:17]
	v_cndmask_b32_e64 v29, v29, v30, s[2:3]
	v_mov_b32_e32 v30, s1
	v_mov_b32_e32 v31, s0
	v_readlane_b32 s0, v81, 31
	v_readlane_b32 s1, v81, 63
	v_cndmask_b32_e64 v30, v30, v31, s[2:3]
	v_mov_b32_e32 v32, s0
	v_mov_b32_e32 v31, s1
	v_readlane_b32 s0, v82, 31
	v_readlane_b32 s1, v82, 63
	v_mul_f32_e32 v84, v41, v26
	v_xor_b32_e32 v41, v39, v65
	v_cndmask_b32_e64 v31, v31, v32, s[2:3]
	v_mov_b32_e32 v32, s1
	v_mov_b32_e32 v33, s0
	v_readlane_b32 s0, v83, 31
	v_readlane_b32 s1, v83, 63
	v_mul_f32_e32 v52, v51, v27
	v_lshl_add_u32 v41, v41, 4, v148
	v_cndmask_b32_e64 v32, v32, v33, s[2:3]
	v_mov_b32_e32 v33, s1
	v_mov_b32_e32 v92, s0
	v_mul_f32_e32 v56, v53, v28
	v_mul_f32_e32 v55, v54, v29
	ds_write_b128 v41, v[42:45] offset:20480
	v_cvt_pk_bf16_f32 v41, v84, v52
	v_cndmask_b32_e64 v33, v33, v92, s[2:3]
	v_mul_f32_e32 v73, v71, v30
	v_mul_f32_e32 v80, v75, v31
	ds_write_b16 v40, v41
	ds_write_b16_d16_hi v40, v41 offset:64
	v_cvt_pk_bf16_f32 v41, v56, v55
	v_mul_f32_e32 v81, v77, v32
	v_mul_f32_e32 v82, v79, v33
	ds_write_b16 v40, v41 offset:128
	ds_write_b16_d16_hi v40, v41 offset:192
	v_cvt_pk_bf16_f32 v41, v73, v80
	ds_write_b16 v40, v41 offset:256
	ds_write_b16_d16_hi v40, v41 offset:320
	v_cvt_pk_bf16_f32 v41, v81, v82
	ds_write_b16 v40, v41 offset:384
	ds_write_b16_d16_hi v40, v41 offset:448
	s_and_saveexec_b64 s[0:1], s[4:5]
	s_cbranch_execz .LBB0_527
	v_add_u32_e32 v41, s17, v183
	ds_write_b128 v41, v[26:29]
	ds_write_b128 v41, v[30:33] offset:16
	s_branch .LBB0_527
